# attention: per-operand counted LDS waits also in the PV sections outside the main loop (prologue/epilogue tiles of each unit)
# baseline (speedup 1.0000x reference)
; #define SBAR() __builtin_amdgcn_sched_barrier(0)
; __device__ __forceinline__ void finishSM(f32x16& p0, f32x16& p1, float alpha, float& l_reg, bf16x8& pa0, bf16x8& pa1, bf16x8& pa2, bf16x8& pa3) {
; #pragma unroll
;   for (int r = 0; r < 16; ++r) p1[r] = __builtin_amdgcn_exp2f(p1[r]);
;   float ps = 0;
; #pragma unroll
;   for (int r = 0; r < 16; ++r) ps += p0[r];
; #pragma unroll
;   for (int r = 0; r < 16; ++r) ps += p1[r];
;   { auto rr = __builtin_amdgcn_permlane32_swap(__float_as_uint(ps), __float_as_uint(ps), false, false);
;     ps = __uint_as_float(rr[0]) + __uint_as_float(rr[1]); }
;   l_reg = l_reg * alpha + ps;
;     ...
;   PK4(p0, 0, pa0); PK4(p0, 8, pa1); PK4(p1, 0, pa2); PK4(p1, 8, pa3);
;     ...
; }
; __device__ __forceinline__ void qkt(f32x16& p0, f32x16& p1, const bf16_t* Ks, const bf16x8* qr, int r32, int hi) {
;   p0 = f32x16{}; p1 = f32x16{};
; #pragma unroll
;   for (int d0 = 0; d0 < 8; ++d0) { int cb = (d0 * 16 + hi * 8) * 2;
;     bf16x8 b0 = *reinterpret_cast<const bf16x8*>((const char*)Ks + KSWZ(r32, cb));
;     bf16x8 b1 = *reinterpret_cast<const bf16x8*>((const char*)Ks + KSWZ(32 + r32, cb));
;     p0 = __builtin_amdgcn_mfma_f32_32x32x16_bf16(b0, qr[d0], p0, 0, 0, 0);
;     p1 = __builtin_amdgcn_mfma_f32_32x32x16_bf16(b1, qr[d0], p1, 0, 0, 0); }
; template <int DA, int DB> __device__ __forceinline__ void pv_pair(f32x16& oa, f32x16& ob, int vb, bf16x8 pa0, bf16x8 pa1, bf16x8 pa2, bf16x8 pa3) {
;     ...
;   { const s16x4 al0 = tr_read<v_rd_off(DA, 0, 0)>(vb), ah0 = tr_read<v_rd_off(DA, 0, 1)>(vb), al1 = tr_read<v_rd_off(DA, 1, 0)>(vb), ah1 = tr_read<v_rd_off(DA, 1, 1)>(vb);
;     const s16x4 bl0 = tr_read<v_rd_off(DB, 0, 0)>(vb), bh0 = tr_read<v_rd_off(DB, 0, 1)>(vb), bl1 = tr_read<v_rd_off(DB, 1, 0)>(vb), bh1 = tr_read<v_rd_off(DB, 1, 1)>(vb);
;     asm volatile("s_waitcnt lgkmcnt(0)" ::: "memory"); SBAR();
;     oa = __builtin_amdgcn_mfma_f32_32x32x16_bf16(pa0, PK(al0, ah0), oa, 0, 0, 0); ob = __builtin_amdgcn_mfma_f32_32x32x16_bf16(pa0, PK(bl0, bh0), ob, 0, 0, 0);
;     oa = __builtin_amdgcn_mfma_f32_32x32x16_bf16(pa1, PK(al1, ah1), oa, 0, 0, 0); ob = __builtin_amdgcn_mfma_f32_32x32x16_bf16(pa1, PK(bl1, bh1), ob, 0, 0, 0); }
.LBB0_456:
	ds_read_b128 v[64:67], v204 offset:49152
	ds_read_b128 v[68:71], v204 offset:57344
	v_exp_f32_e32 v154, v154
	v_exp_f32_e32 v155, v155
	v_exp_f32_e32 v152, v152
	s_waitcnt lgkmcnt(1)
	v_mfma_f32_32x32x16_bf16 v[80:95], v[64:67], v[124:127], 0
	v_exp_f32_e32 v153, v153
	v_exp_f32_e32 v148, v148
	s_waitcnt lgkmcnt(0)
	v_mfma_f32_32x32x16_bf16 v[64:79], v[68:71], v[124:127], 0
	ds_read_b128 v[124:127], v205 offset:49152
	ds_read_b128 v[128:131], v205 offset:57344
	ds_read_b128 v[132:135], v206 offset:49152
	ds_read_b128 v[136:139], v206 offset:57344
	s_waitcnt lgkmcnt(3)
	v_mfma_f32_32x32x16_bf16 v[80:95], v[124:127], v[120:123], v[80:95]
	ds_read_b128 v[124:127], v207 offset:49152
	ds_read_b128 v[140:143], v207 offset:57344
	ds_read_b128 v[218:221], v208 offset:49152
	ds_read_b128 v[222:225], v208 offset:57344
	ds_read_b128 v[226:229], v209 offset:49152
	ds_read_b128 v[230:233], v209 offset:57344
	ds_read_b128 v[234:237], v210 offset:49152
	ds_read_b128 v[238:241], v210 offset:57344
	s_waitcnt lgkmcnt(10)
	v_mfma_f32_32x32x16_bf16 v[64:79], v[128:131], v[120:123], v[64:79]
	ds_read_b128 v[120:123], v211 offset:49152
	ds_read_b128 v[128:131], v211 offset:57344
	s_waitcnt lgkmcnt(11)
	v_mfma_f32_32x32x16_bf16 v[80:95], v[132:135], v[116:119], v[80:95]
	v_exp_f32_e32 v132, v149
	v_exp_f32_e32 v133, v146
	v_exp_f32_e32 v134, v147
	v_exp_f32_e32 v135, v144
	v_exp_f32_e32 v144, v145
	v_exp_f32_e32 v145, v158
	v_exp_f32_e32 v146, v159
	s_waitcnt lgkmcnt(10)
	v_mfma_f32_32x32x16_bf16 v[64:79], v[136:139], v[116:119], v[64:79]
	v_add_f32_e32 v116, 0, v175
	v_add_f32_e32 v116, v191, v116
	v_add_f32_e32 v116, v173, v116
	v_add_f32_e32 v116, v190, v116
	v_add_f32_e32 v116, v172, v116
	v_add_f32_e32 v116, v174, v116
	v_add_f32_e32 v116, v170, v116
	s_waitcnt lgkmcnt(9)
	v_mfma_f32_32x32x16_bf16 v[80:95], v[124:127], v[112:115], v[80:95]
	v_add_f32_e32 v116, v171, v116
	v_add_f32_e32 v116, v167, v116
	v_add_f32_e32 v116, v169, v116
	v_exp_f32_e32 v118, v156
	v_exp_f32_e32 v119, v157
	v_exp_f32_e32 v136, v150
	v_exp_f32_e32 v137, v151
	s_waitcnt lgkmcnt(8)
	v_mfma_f32_32x32x16_bf16 v[64:79], v[140:143], v[112:115], v[64:79]
	v_add_f32_e32 v112, v166, v116
	v_add_f32_e32 v112, v168, v112
	v_add_f32_e32 v112, v163, v112
	v_add_f32_e32 v112, v165, v112
	v_add_f32_e32 v112, v162, v112
	v_add_f32_e32 v112, v164, v112
	v_add_f32_e32 v112, v154, v112
	s_waitcnt lgkmcnt(7)
	v_mfma_f32_32x32x16_bf16 v[80:95], v[218:221], v[108:111], v[80:95]
	v_add_f32_e32 v112, v155, v112
	v_add_f32_e32 v112, v152, v112
	v_add_f32_e32 v112, v153, v112
	v_add_f32_e32 v112, v148, v112
	v_add_f32_e32 v112, v132, v112
	v_add_f32_e32 v112, v133, v112
	v_add_f32_e32 v112, v134, v112
	s_waitcnt lgkmcnt(6)
	v_mfma_f32_32x32x16_bf16 v[64:79], v[222:225], v[108:111], v[64:79]
	v_add_f32_e32 v108, v135, v112
	v_add_f32_e32 v108, v144, v108
	v_add_f32_e32 v108, v145, v108
	v_add_f32_e32 v108, v146, v108
	v_add_f32_e32 v108, v118, v108
	v_add_f32_e32 v108, v119, v108
	v_add_f32_e32 v108, v136, v108
	s_waitcnt lgkmcnt(5)
	v_mfma_f32_32x32x16_bf16 v[80:95], v[226:229], v[104:107], v[80:95]
	v_add_f32_e32 v108, v137, v108
	v_mov_b32_e32 v109, v108
	s_nop 1
	v_permlane32_swap_b32_e32 v108, v109
	v_cvt_pk_bf16_f32 v110, v175, v191
	v_cvt_pk_bf16_f32 v111, v173, v190
	v_cvt_pk_bf16_f32 v112, v172, v174
	s_waitcnt lgkmcnt(4)
	v_mfma_f32_32x32x16_bf16 v[64:79], v[230:233], v[104:107], v[64:79]
	v_cvt_pk_bf16_f32 v113, v170, v171
	v_cvt_pk_bf16_f32 v104, v167, v169
	v_cvt_pk_bf16_f32 v105, v166, v168
	v_cvt_pk_bf16_f32 v106, v163, v165
	v_cvt_pk_bf16_f32 v107, v162, v164
	v_cvt_pk_bf16_f32 v114, v154, v155
	v_cvt_pk_bf16_f32 v115, v152, v153
	s_waitcnt lgkmcnt(3)
	v_mfma_f32_32x32x16_bf16 v[80:95], v[234:237], v[100:103], v[80:95]
	v_cvt_pk_bf16_f32 v116, v148, v132
	v_cvt_pk_bf16_f32 v117, v133, v134
	v_permlane32_swap_b32_e32 v110, v112
	v_permlane32_swap_b32_e32 v111, v113
	v_permlane32_swap_b32_e32 v104, v106
	s_waitcnt lgkmcnt(2)
	v_mfma_f32_32x32x16_bf16 v[64:79], v[238:241], v[100:103], v[64:79]
	v_cvt_pk_bf16_f32 v100, v135, v144
	v_cvt_pk_bf16_f32 v101, v145, v146
	v_cvt_pk_bf16_f32 v102, v118, v119
	v_cvt_pk_bf16_f32 v103, v136, v137
	v_permlane32_swap_b32_e32 v105, v107
	v_permlane32_swap_b32_e32 v114, v116
	s_waitcnt lgkmcnt(1)
	v_mfma_f32_32x32x16_bf16 v[80:95], v[120:123], v[96:99], v[80:95]
	v_permlane32_swap_b32_e32 v115, v117
	v_permlane32_swap_b32_e32 v100, v102
	v_permlane32_swap_b32_e32 v101, v103
	s_waitcnt lgkmcnt(0)
	v_mfma_f32_32x32x16_bf16 v[64:79], v[128:131], v[96:99], v[64:79]
	ds_read_b64_tr_b16 v[96:97], v196 offset:0
	ds_read_b64_tr_b16 v[98:99], v196 offset:0x800
	ds_read_b64_tr_b16 v[118:119], v196 offset:0x1000
	ds_read_b64_tr_b16 v[120:121], v196 offset:0x1800
	ds_read_b64_tr_b16 v[122:123], v196 offset:0x200
	ds_read_b64_tr_b16 v[124:125], v196 offset:0xa00
	ds_read_b64_tr_b16 v[126:127], v196 offset:0x1200
	ds_read_b64_tr_b16 v[128:129], v196 offset:0x1a00
	s_nop 0
	s_waitcnt lgkmcnt(6)
	v_mfma_f32_32x32x16_bf16 v[0:15], v[110:113], v[96:99], v[0:15]
	ds_read_b64_tr_b16 v[96:97], v196 offset:0x2000
	ds_read_b64_tr_b16 v[98:99], v196 offset:0x2800
	s_waitcnt lgkmcnt(4)
	v_mfma_f32_32x32x16_bf16 v[48:63], v[110:113], v[122:125], v[48:63]
	v_mfma_f32_32x32x16_bf16 v[0:15], v[104:107], v[118:121], v[0:15]
	ds_read_b64_tr_b16 v[118:119], v196 offset:0x3000
	ds_read_b64_tr_b16 v[120:121], v196 offset:0x3800
	ds_read_b64_tr_b16 v[122:123], v196 offset:0x2200
	ds_read_b64_tr_b16 v[124:125], v196 offset:0x2a00
	ds_read_b64_tr_b16 v[130:131], v196 offset:0x3200
	ds_read_b64_tr_b16 v[132:133], v196 offset:0x3a00
	s_waitcnt lgkmcnt(8)
; __device__ __forceinline__ void partialSM(f32x16& p0, f32x16& p1, float& m_reg, float& mn, float& alpha) {
;   constexpr float C = SCALE * 1.4426950408889634f;
;   float pmax = p0[0];
; #pragma unroll
;   for (int r = 1; r < 16; ++r) pmax = fmaxf(pmax, p0[r]);
; #pragma unroll
;   for (int r = 0; r < 16; ++r) pmax = fmaxf(pmax, p1[r]);
;   { auto rr = __builtin_amdgcn_permlane32_swap(__float_as_uint(pmax), __float_as_uint(pmax), false, false);
;     pmax = fmaxf(__uint_as_float(rr[0]), __uint_as_float(rr[1])); }
; template <int DA, int DB> __device__ __forceinline__ void pv_pair(f32x16& oa, f32x16& ob, int vb, bf16x8 pa0, bf16x8 pa1, bf16x8 pa2, bf16x8 pa3) {
;     ...
;   { const s16x4 al0 = tr_read<v_rd_off(DA, 0, 0)>(vb), ah0 = tr_read<v_rd_off(DA, 0, 1)>(vb), al1 = tr_read<v_rd_off(DA, 1, 0)>(vb), ah1 = tr_read<v_rd_off(DA, 1, 1)>(vb);
;     const s16x4 bl0 = tr_read<v_rd_off(DB, 0, 0)>(vb), bh0 = tr_read<v_rd_off(DB, 0, 1)>(vb), bl1 = tr_read<v_rd_off(DB, 1, 0)>(vb), bh1 = tr_read<v_rd_off(DB, 1, 1)>(vb);
;     asm volatile("s_waitcnt lgkmcnt(0)" ::: "memory"); SBAR();
;     oa = __builtin_amdgcn_mfma_f32_32x32x16_bf16(pa0, PK(al0, ah0), oa, 0, 0, 0); ob = __builtin_amdgcn_mfma_f32_32x32x16_bf16(pa0, PK(bl0, bh0), ob, 0, 0, 0);
;     oa = __builtin_amdgcn_mfma_f32_32x32x16_bf16(pa1, PK(al1, ah1), oa, 0, 0, 0); ob = __builtin_amdgcn_mfma_f32_32x32x16_bf16(pa1, PK(bl1, bh1), ob, 0, 0, 0); }
;   { const s16x4 al2 = tr_read<v_rd_off(DA, 2, 0)>(vb), ah2 = tr_read<v_rd_off(DA, 2, 1)>(vb), al3 = tr_read<v_rd_off(DA, 3, 0)>(vb), ah3 = tr_read<v_rd_off(DA, 3, 1)>(vb);
;     const s16x4 bl2 = tr_read<v_rd_off(DB, 2, 0)>(vb), bh2 = tr_read<v_rd_off(DB, 2, 1)>(vb), bl3 = tr_read<v_rd_off(DB, 3, 0)>(vb), bh3 = tr_read<v_rd_off(DB, 3, 1)>(vb);
;     asm volatile("s_waitcnt lgkmcnt(0)" ::: "memory"); SBAR();
;     oa = __builtin_amdgcn_mfma_f32_32x32x16_bf16(pa2, PK(al2, ah2), oa, 0, 0, 0); ob = __builtin_amdgcn_mfma_f32_32x32x16_bf16(pa2, PK(bl2, bh2), ob, 0, 0, 0);
;     oa = __builtin_amdgcn_mfma_f32_32x32x16_bf16(pa3, PK(al3, ah3), oa, 0, 0, 0); ob = __builtin_amdgcn_mfma_f32_32x32x16_bf16(pa3, PK(bl3, bh3), ob, 0, 0, 0); }
;     ...
; }
; __device__ __forceinline__ void pv_d0(f32x16* o, int vb, bf16x8 pa0, bf16x8 pa1, bf16x8 pa2, bf16x8 pa3) {
;   pv_pair<0, 1>(o[0], o[1], vb, pa0, pa1, pa2, pa3); pv_pair<2, 3>(o[2], o[3], vb, pa0, pa1, pa2, pa3);
	v_mfma_f32_32x32x16_bf16 v[48:63], v[104:107], v[126:129], v[48:63]
	s_waitcnt lgkmcnt(6)
	v_mfma_f32_32x32x16_bf16 v[0:15], v[114:117], v[96:99], v[0:15]
	ds_read_b64_tr_b16 v[96:97], v196 offset:0x400
	ds_read_b64_tr_b16 v[98:99], v196 offset:0xc00
	s_waitcnt lgkmcnt(4)
	v_mfma_f32_32x32x16_bf16 v[48:63], v[114:117], v[122:125], v[48:63]
	v_mfma_f32_32x32x16_bf16 v[0:15], v[100:103], v[118:121], v[0:15]
	ds_read_b64_tr_b16 v[118:119], v196 offset:0x1400
	ds_read_b64_tr_b16 v[120:121], v196 offset:0x1c00
	ds_read_b64_tr_b16 v[122:123], v196 offset:0x600
	ds_read_b64_tr_b16 v[124:125], v196 offset:0xe00
	ds_read_b64_tr_b16 v[126:127], v196 offset:0x1600
	ds_read_b64_tr_b16 v[128:129], v196 offset:0x1e00
	s_waitcnt lgkmcnt(8)
	v_mfma_f32_32x32x16_bf16 v[48:63], v[100:103], v[130:133], v[48:63]
	s_waitcnt lgkmcnt(6)
	v_mfma_f32_32x32x16_bf16 v[32:47], v[110:113], v[96:99], v[32:47]
	ds_read_b64_tr_b16 v[96:97], v196 offset:0x2400
	ds_read_b64_tr_b16 v[98:99], v196 offset:0x2c00
	s_waitcnt lgkmcnt(4)
	v_mfma_f32_32x32x16_bf16 v[16:31], v[110:113], v[122:125], v[16:31]
	ds_read_b64_tr_b16 v[110:111], v196 offset:0x3400
	ds_read_b64_tr_b16 v[112:113], v196 offset:0x3c00
	v_mfma_f32_32x32x16_bf16 v[32:47], v[104:107], v[118:121], v[32:47]
	ds_read_b64_tr_b16 v[118:119], v196 offset:0x2600
	ds_read_b64_tr_b16 v[120:121], v196 offset:0x2e00
	ds_read_b64_tr_b16 v[122:123], v196 offset:0x3600
	ds_read_b64_tr_b16 v[124:125], v196 offset:0x3e00
	s_waitcnt lgkmcnt(8)
	v_mfma_f32_32x32x16_bf16 v[16:31], v[104:107], v[126:129], v[16:31]
	v_max_f32_e32 v104, v81, v81
	v_max_f32_e32 v105, v80, v80
	v_max_f32_e32 v104, v105, v104
	v_max3_f32 v104, v104, v82, v83
	v_max3_f32 v104, v104, v84, v85
	s_waitcnt lgkmcnt(6)
	v_mfma_f32_32x32x16_bf16 v[32:47], v[114:117], v[96:99], v[32:47]
	v_max3_f32 v96, v104, v86, v87
	v_max3_f32 v96, v96, v88, v89
	v_max3_f32 v96, v96, v90, v91
	v_max3_f32 v96, v96, v92, v93
	v_max3_f32 v96, v96, v94, v95
	v_max3_f32 v96, v96, v64, v65
	v_max3_f32 v96, v96, v66, v67
	v_max3_f32 v96, v96, v68, v69
	v_max3_f32 v96, v96, v70, v71
	v_max3_f32 v96, v96, v72, v73
	s_waitcnt lgkmcnt(2)
	v_mfma_f32_32x32x16_bf16 v[16:31], v[114:117], v[118:121], v[16:31]
	v_max3_f32 v96, v96, v74, v75
	v_max3_f32 v96, v96, v76, v77
	v_max3_f32 v96, v96, v78, v79
	v_mov_b32_e32 v97, v96
	s_nop 1
	v_permlane32_swap_b32_e32 v96, v97
	v_max_f32_e32 v97, v97, v97
	v_max_f32_e32 v96, v96, v96
	v_max_f32_e32 v96, v96, v97
	v_max_f32_e32 v97, v160, v160
	v_max_f32_e32 v97, v97, v96
	v_mfma_f32_32x32x16_bf16 v[32:47], v[100:103], v[110:113], v[32:47]
	v_sub_f32_e32 v98, v96, v160
	v_sub_f32_e32 v96, v160, v97
	v_mul_f32_e32 v96, 0x3e0293ee, v96
	v_exp_f32_e32 v96, v96
	v_cmp_ge_f32_e32 vcc, s67, v98
	s_cmp_eq_u64 vcc, exec
	s_cselect_b64 s[6:7], -1, 0
	s_waitcnt lgkmcnt(0)
	v_mfma_f32_32x32x16_bf16 v[16:31], v[100:103], v[122:125], v[16:31]
	v_cndmask_b32_e64 v96, v96, 1.0, s[6:7]
	v_cmp_gt_f32_e32 vcc, 1.0, v96
	s_barrier
	s_cbranch_vccz .LBB0_460
	s_and_saveexec_b64 s[18:19], s[4:5]
	ds_write_b32 v198, v96 offset:128
	s_or_b64 exec, exec, s[18:19]
	s_waitcnt lgkmcnt(0)
	v_add_u32_e32 v106, v195, v197
	ds_read_b128 v[98:101], v106 offset:224
	ds_read_b128 v[102:105], v106 offset:192
	ds_read_b128 v[110:113], v106 offset:160
	ds_read_b128 v[114:117], v106 offset:128
	s_waitcnt lgkmcnt(3)
	v_pk_mul_f32 v[12:13], v[12:13], v[98:99]
	s_waitcnt lgkmcnt(2)
	v_pk_mul_f32 v[8:9], v[8:9], v[102:103]
	s_waitcnt lgkmcnt(1)
	v_pk_mul_f32 v[4:5], v[4:5], v[110:111]
	v_pk_mul_f32 v[14:15], v[14:15], v[100:101]
	v_pk_mul_f32 v[10:11], v[10:11], v[104:105]
	v_pk_mul_f32 v[6:7], v[6:7], v[112:113]
	s_waitcnt lgkmcnt(0)
	v_pk_mul_f32 v[2:3], v[2:3], v[116:117]
	v_pk_mul_f32 v[0:1], v[0:1], v[114:115]
	v_pk_mul_f32 v[60:61], v[60:61], v[98:99]
	v_pk_mul_f32 v[56:57], v[56:57], v[102:103]
	v_pk_mul_f32 v[52:53], v[52:53], v[110:111]
	v_pk_mul_f32 v[62:63], v[62:63], v[100:101]
	v_pk_mul_f32 v[58:59], v[58:59], v[104:105]
	v_pk_mul_f32 v[54:55], v[54:55], v[112:113]
	v_pk_mul_f32 v[50:51], v[50:51], v[116:117]
	v_pk_mul_f32 v[48:49], v[48:49], v[114:115]
	v_pk_mul_f32 v[44:45], v[44:45], v[98:99]
	v_pk_mul_f32 v[40:41], v[40:41], v[102:103]
	v_pk_mul_f32 v[36:37], v[36:37], v[110:111]
	v_pk_mul_f32 v[46:47], v[46:47], v[100:101]
	v_pk_mul_f32 v[42:43], v[42:43], v[104:105]
	v_pk_mul_f32 v[38:39], v[38:39], v[112:113]
	v_pk_mul_f32 v[34:35], v[34:35], v[116:117]
	v_pk_mul_f32 v[32:33], v[32:33], v[114:115]
	v_pk_mul_f32 v[28:29], v[28:29], v[98:99]
	v_pk_mul_f32 v[24:25], v[24:25], v[102:103]
	v_pk_mul_f32 v[20:21], v[20:21], v[110:111]
	v_pk_mul_f32 v[30:31], v[30:31], v[100:101]
	v_pk_mul_f32 v[26:27], v[26:27], v[104:105]
	v_pk_mul_f32 v[22:23], v[22:23], v[112:113]
	v_pk_mul_f32 v[18:19], v[18:19], v[116:117]
	v_pk_mul_f32 v[16:17], v[16:17], v[114:115]
; #define SBAR() __builtin_amdgcn_sched_barrier(0)
; __device__ __forceinline__ void partialSM(f32x16& p0, f32x16& p1, float& m_reg, float& mn, float& alpha) {
;     ...
;   if (__builtin_expect(__all(pmax - m_reg <= THR / SCALE), 1)) { mn = m_reg; alpha = 1.f; }
;   else { mn = fmaxf(m_reg, pmax); alpha = __builtin_amdgcn_exp2f((m_reg - mn) * C); m_reg = mn; }
;   float mnC = -mn * C;
; #pragma unroll
;   for (int r = 0; r < 16; ++r) p0[r] = fmaf(p0[r], C, mnC);
; #pragma unroll
;   for (int r = 0; r < 16; ++r) p1[r] = fmaf(p1[r], C, mnC);
; #pragma unroll
;   for (int r = 0; r < 16; ++r) p0[r] = __builtin_amdgcn_exp2f(p0[r]);
; }
; __device__ __forceinline__ void finishSM(f32x16& p0, f32x16& p1, float alpha, float& l_reg, bf16x8& pa0, bf16x8& pa1, bf16x8& pa2, bf16x8& pa3) {
; #pragma unroll
;   for (int r = 0; r < 16; ++r) p1[r] = __builtin_amdgcn_exp2f(p1[r]);
;   float ps = 0;
; #pragma unroll
;   for (int r = 0; r < 16; ++r) ps += p0[r];
; #pragma unroll
;   for (int r = 0; r < 16; ++r) ps += p1[r];
;   { auto rr = __builtin_amdgcn_permlane32_swap(__float_as_uint(ps), __float_as_uint(ps), false, false);
;     ps = __uint_as_float(rr[0]) + __uint_as_float(rr[1]); }
;   l_reg = l_reg * alpha + ps;
;     ...
;   PK4(p0, 0, pa0); PK4(p0, 8, pa1); PK4(p1, 0, pa2); PK4(p1, 8, pa3);
;     ...
; }
; template <int DA, int DB> __device__ __forceinline__ void pv_pair(f32x16& oa, f32x16& ob, int vb, bf16x8 pa0, bf16x8 pa1, bf16x8 pa2, bf16x8 pa3) {
;     ...
;   { const s16x4 al0 = tr_read<v_rd_off(DA, 0, 0)>(vb), ah0 = tr_read<v_rd_off(DA, 0, 1)>(vb), al1 = tr_read<v_rd_off(DA, 1, 0)>(vb), ah1 = tr_read<v_rd_off(DA, 1, 1)>(vb);
;     const s16x4 bl0 = tr_read<v_rd_off(DB, 0, 0)>(vb), bh0 = tr_read<v_rd_off(DB, 0, 1)>(vb), bl1 = tr_read<v_rd_off(DB, 1, 0)>(vb), bh1 = tr_read<v_rd_off(DB, 1, 1)>(vb);
;     asm volatile("s_waitcnt lgkmcnt(0)" ::: "memory"); SBAR();
;     oa = __builtin_amdgcn_mfma_f32_32x32x16_bf16(pa0, PK(al0, ah0), oa, 0, 0, 0); ob = __builtin_amdgcn_mfma_f32_32x32x16_bf16(pa0, PK(bl0, bh0), ob, 0, 0, 0);
;     oa = __builtin_amdgcn_mfma_f32_32x32x16_bf16(pa1, PK(al1, ah1), oa, 0, 0, 0); ob = __builtin_amdgcn_mfma_f32_32x32x16_bf16(pa1, PK(bl1, bh1), ob, 0, 0, 0); }
;   { const s16x4 al2 = tr_read<v_rd_off(DA, 2, 0)>(vb), ah2 = tr_read<v_rd_off(DA, 2, 1)>(vb), al3 = tr_read<v_rd_off(DA, 3, 0)>(vb), ah3 = tr_read<v_rd_off(DA, 3, 1)>(vb);
.LBB0_460:
	v_cndmask_b32_e64 v97, v97, v160, s[6:7]
	v_mul_f32_e32 v97, 0xbe0293ee, v97
	v_fmamk_f32 v80, v80, 0x3e0293ee, v97
	v_fmamk_f32 v81, v81, 0x3e0293ee, v97
	v_fmamk_f32 v98, v82, 0x3e0293ee, v97
	v_exp_f32_e32 v82, v80
	v_fmamk_f32 v99, v84, 0x3e0293ee, v97
	v_exp_f32_e32 v84, v81
	v_fmamk_f32 v83, v83, 0x3e0293ee, v97
	v_exp_f32_e32 v80, v98
	v_fmamk_f32 v64, v64, 0x3e0293ee, v97
	v_exp_f32_e32 v83, v83
	v_fmamk_f32 v100, v85, 0x3e0293ee, v97
	v_fmamk_f32 v111, v94, 0x3e0293ee, v97
	v_fmamk_f32 v94, v75, 0x3e0293ee, v97
	v_exp_f32_e32 v75, v99
	v_exp_f32_e32 v98, v64
	v_add_f32_e32 v64, 0, v82
	v_fmamk_f32 v101, v86, 0x3e0293ee, v97
	v_exp_f32_e32 v81, v100
	v_add_f32_e32 v64, v84, v64
	v_fmamk_f32 v102, v87, 0x3e0293ee, v97
	v_fmamk_f32 v110, v93, 0x3e0293ee, v97
	v_fmamk_f32 v93, v74, 0x3e0293ee, v97
	v_exp_f32_e32 v74, v101
	v_add_f32_e32 v64, v80, v64
	v_fmamk_f32 v103, v88, 0x3e0293ee, v97
	v_fmamk_f32 v112, v95, 0x3e0293ee, v97
	v_fmamk_f32 v95, v76, 0x3e0293ee, v97
	v_exp_f32_e32 v76, v102
	v_add_f32_e32 v64, v83, v64
	v_fmamk_f32 v104, v89, 0x3e0293ee, v97
	v_fmamk_f32 v105, v90, 0x3e0293ee, v97
	v_fmamk_f32 v90, v71, 0x3e0293ee, v97
	v_exp_f32_e32 v71, v103
	v_add_f32_e32 v64, v75, v64
	v_fmamk_f32 v107, v92, 0x3e0293ee, v97
	v_fmamk_f32 v92, v73, 0x3e0293ee, v97
	v_exp_f32_e32 v73, v104
	v_add_f32_e32 v64, v81, v64
	v_fmamk_f32 v106, v91, 0x3e0293ee, v97
	v_fmamk_f32 v88, v69, 0x3e0293ee, v97
	v_exp_f32_e32 v69, v105
	v_add_f32_e32 v64, v74, v64
	v_fmamk_f32 v91, v72, 0x3e0293ee, v97
	v_exp_f32_e32 v72, v106
	v_add_f32_e32 v64, v76, v64
	v_fmamk_f32 v86, v67, 0x3e0293ee, v97
	v_exp_f32_e32 v67, v107
	v_add_f32_e32 v64, v71, v64
	v_fmamk_f32 v89, v70, 0x3e0293ee, v97
	v_exp_f32_e32 v70, v110
	v_add_f32_e32 v64, v73, v64
	v_fmamk_f32 v85, v66, 0x3e0293ee, v97
	v_exp_f32_e32 v66, v111
	v_add_f32_e32 v64, v69, v64
	v_fmamk_f32 v87, v68, 0x3e0293ee, v97
	v_exp_f32_e32 v68, v112
	v_add_f32_e32 v64, v72, v64
	v_fmamk_f32 v65, v65, 0x3e0293ee, v97
	v_add_f32_e32 v64, v67, v64
	v_exp_f32_e32 v99, v65
	v_add_f32_e32 v64, v70, v64
	v_exp_f32_e32 v85, v85
	v_add_f32_e32 v64, v66, v64
	v_exp_f32_e32 v86, v86
	v_add_f32_e32 v64, v68, v64
	v_exp_f32_e32 v87, v87
	v_add_f32_e32 v64, v98, v64
	v_exp_f32_e32 v88, v88
	v_add_f32_e32 v64, v99, v64
	v_exp_f32_e32 v89, v89
	v_add_f32_e32 v64, v85, v64
	v_exp_f32_e32 v90, v90
	v_add_f32_e32 v64, v86, v64
	v_exp_f32_e32 v91, v91
	v_add_f32_e32 v64, v87, v64
	v_exp_f32_e32 v92, v92
	v_add_f32_e32 v64, v88, v64
	v_exp_f32_e32 v93, v93
	v_add_f32_e32 v64, v89, v64
	v_exp_f32_e32 v94, v94
	v_add_f32_e32 v64, v90, v64
	v_fmamk_f32 v77, v77, 0x3e0293ee, v97
	v_exp_f32_e32 v95, v95
	v_add_f32_e32 v64, v91, v64
	v_fmamk_f32 v78, v78, 0x3e0293ee, v97
	v_exp_f32_e32 v100, v77
	v_add_f32_e32 v64, v92, v64
	v_fmac_f32_e32 v97, 0x3e0293ee, v79
	v_exp_f32_e32 v101, v78
	v_add_f32_e32 v64, v93, v64
	v_exp_f32_e32 v97, v97
	v_add_f32_e32 v64, v94, v64
	v_add_f32_e32 v64, v95, v64
	v_add_f32_e32 v64, v100, v64
	v_add_f32_e32 v64, v101, v64
	v_add_f32_e32 v64, v97, v64
	v_mov_b32_e32 v65, v64
	s_nop 1
	v_permlane32_swap_b32_e32 v64, v65
	v_cvt_pk_bf16_f32 v78, v82, v84
	v_cvt_pk_bf16_f32 v79, v80, v83
	v_cvt_pk_bf16_f32 v80, v75, v81
	v_cvt_pk_bf16_f32 v81, v74, v76
	v_cvt_pk_bf16_f32 v74, v71, v73
	v_cvt_pk_bf16_f32 v75, v69, v72
	v_cvt_pk_bf16_f32 v76, v67, v70
	v_cvt_pk_bf16_f32 v77, v66, v68
	v_cvt_pk_bf16_f32 v66, v98, v99
	v_cvt_pk_bf16_f32 v67, v85, v86
	v_cvt_pk_bf16_f32 v68, v87, v88
	v_cvt_pk_bf16_f32 v69, v89, v90
	v_cvt_pk_bf16_f32 v70, v91, v92
	v_cvt_pk_bf16_f32 v71, v93, v94
	v_cvt_pk_bf16_f32 v72, v95, v100
	v_cvt_pk_bf16_f32 v73, v101, v97
	s_nop 0
	v_permlane32_swap_b32_e32 v78, v80
	v_permlane32_swap_b32_e32 v79, v81
	v_permlane32_swap_b32_e32 v74, v76
	v_permlane32_swap_b32_e32 v75, v77
	v_permlane32_swap_b32_e32 v66, v68
	v_permlane32_swap_b32_e32 v67, v69
	v_permlane32_swap_b32_e32 v70, v72
	v_permlane32_swap_b32_e32 v71, v73
	ds_read_b64_tr_b16 v[82:83], v199 offset:0
	ds_read_b64_tr_b16 v[84:85], v199 offset:0x800
	ds_read_b64_tr_b16 v[86:87], v199 offset:0x1000
	ds_read_b64_tr_b16 v[88:89], v199 offset:0x1800
	ds_read_b64_tr_b16 v[90:91], v199 offset:0x200
	ds_read_b64_tr_b16 v[92:93], v199 offset:0xa00
	ds_read_b64_tr_b16 v[98:99], v199 offset:0x1200
	ds_read_b64_tr_b16 v[100:101], v199 offset:0x1a00
	s_nop 0
	s_waitcnt lgkmcnt(6)
	v_mfma_f32_32x32x16_bf16 v[0:15], v[78:81], v[82:85], v[0:15]
	ds_read_b64_tr_b16 v[82:83], v199 offset:0x2000
	ds_read_b64_tr_b16 v[84:85], v199 offset:0x2800
	s_waitcnt lgkmcnt(4)
	v_mfma_f32_32x32x16_bf16 v[48:63], v[78:81], v[90:93], v[48:63]
	v_mfma_f32_32x32x16_bf16 v[0:15], v[74:77], v[86:89], v[0:15]
	ds_read_b64_tr_b16 v[86:87], v199 offset:0x3000
	ds_read_b64_tr_b16 v[88:89], v199 offset:0x3800
	ds_read_b64_tr_b16 v[90:91], v199 offset:0x2200
	ds_read_b64_tr_b16 v[92:93], v199 offset:0x2a00
	ds_read_b64_tr_b16 v[102:103], v199 offset:0x3200
	ds_read_b64_tr_b16 v[104:105], v199 offset:0x3a00
	s_waitcnt lgkmcnt(8)
	v_mfma_f32_32x32x16_bf16 v[48:63], v[74:77], v[98:101], v[48:63]
	s_waitcnt lgkmcnt(6)
	v_mfma_f32_32x32x16_bf16 v[0:15], v[66:69], v[82:85], v[0:15]
	ds_read_b64_tr_b16 v[82:83], v199 offset:0x400
	ds_read_b64_tr_b16 v[84:85], v199 offset:0xc00
	s_waitcnt lgkmcnt(4)
	v_mfma_f32_32x32x16_bf16 v[48:63], v[66:69], v[90:93], v[48:63]
	v_mfma_f32_32x32x16_bf16 v[0:15], v[70:73], v[86:89], v[0:15]
	ds_read_b64_tr_b16 v[86:87], v199 offset:0x1400
	ds_read_b64_tr_b16 v[88:89], v199 offset:0x1c00
	ds_read_b64_tr_b16 v[90:91], v199 offset:0x600
	ds_read_b64_tr_b16 v[92:93], v199 offset:0xe00
	ds_read_b64_tr_b16 v[98:99], v199 offset:0x1600
	ds_read_b64_tr_b16 v[100:101], v199 offset:0x1e00
	s_waitcnt lgkmcnt(8)
	v_mfma_f32_32x32x16_bf16 v[48:63], v[70:73], v[102:105], v[48:63]
	s_waitcnt lgkmcnt(6)
	v_mfma_f32_32x32x16_bf16 v[32:47], v[78:81], v[82:85], v[32:47]
	s_waitcnt lgkmcnt(2)
	v_mfma_f32_32x32x16_bf16 v[16:31], v[78:81], v[90:93], v[16:31]
	ds_read_b64_tr_b16 v[78:79], v199 offset:0x2400
	ds_read_b64_tr_b16 v[80:81], v199 offset:0x2c00
	ds_read_b64_tr_b16 v[82:83], v199 offset:0x3400
	ds_read_b64_tr_b16 v[84:85], v199 offset:0x3c00
	v_mfma_f32_32x32x16_bf16 v[32:47], v[74:77], v[86:89], v[32:47]
	ds_read_b64_tr_b16 v[86:87], v199 offset:0x2600
	ds_read_b64_tr_b16 v[88:89], v199 offset:0x2e00
	ds_read_b64_tr_b16 v[90:91], v199 offset:0x3600
	ds_read_b64_tr_b16 v[92:93], v199 offset:0x3e00
	s_waitcnt lgkmcnt(8)
	v_mfma_f32_32x32x16_bf16 v[16:31], v[74:77], v[98:101], v[16:31]
	s_waitcnt lgkmcnt(6)
	v_mfma_f32_32x32x16_bf16 v[32:47], v[66:69], v[78:81], v[32:47]
	s_waitcnt lgkmcnt(2)
	v_mfma_f32_32x32x16_bf16 v[16:31], v[66:69], v[86:89], v[16:31]
	v_mfma_f32_32x32x16_bf16 v[32:47], v[70:73], v[82:85], v[32:47]
	s_waitcnt lgkmcnt(0)
	v_mfma_f32_32x32x16_bf16 v[16:31], v[70:73], v[90:93], v[16:31]
	s_and_saveexec_b64 s[6:7], s[4:5]
	s_cbranch_execz .LBB0_434
; #define SBAR() __builtin_amdgcn_sched_barrier(0)
; #define RESC(a) do { if (__any((a) < 1.f)) { if (hi == 0) al_l[r32] = (a); asm volatile("s_waitcnt lgkmcnt(0)" ::: "memory"); \
;     _Pragma("unroll") for (int d = 0; d < 4; ++d) _Pragma("unroll") for (int r = 0; r < 16; ++r) o[d][r] *= al_l[crow(r, hi)]; } } while (0)
; __device__ __forceinline__ void attn_dense_body(const bf16_t* __restrict__ Qb, const bf16_t* __restrict__ Kh, const bf16_t* __restrict__ Vh,
;                                                 bf16_t* __restrict__ Ob, int seq, char* lds, const int tid) {
;     ...
;   __syncthreads(); RESC(alB);
;   finishSM(pB0, pB1, alB, l_reg, pa0, pa1, pa2, pa3); SBAR();
;   pv_d0(o, vb0 + (int)SHM_V, pa0, pa1, pa2, pa3);
;   if (hi == 0) li_l[r32] = l_reg; asm volatile("s_waitcnt lgkmcnt(0)" ::: "memory");
	v_add_f32_e32 v66, v108, v109
	v_fmac_f32_e32 v66, v213, v161
	v_add_f32_e32 v64, v64, v65
	v_fmac_f32_e32 v64, v66, v96
	ds_write_b32 v198, v64
	s_branch .LBB0_434

; #define SBAR() __builtin_amdgcn_sched_barrier(0)
; __device__ __forceinline__ void finishSM(f32x16& p0, f32x16& p1, float alpha, float& l_reg, bf16x8& pa0, bf16x8& pa1, bf16x8& pa2, bf16x8& pa3) {
; #pragma unroll
;   for (int r = 0; r < 16; ++r) p1[r] = __builtin_amdgcn_exp2f(p1[r]);
;   float ps = 0;
; #pragma unroll
;   for (int r = 0; r < 16; ++r) ps += p0[r];
; #pragma unroll
;   for (int r = 0; r < 16; ++r) ps += p1[r];
;   { auto rr = __builtin_amdgcn_permlane32_swap(__float_as_uint(ps), __float_as_uint(ps), false, false);
;     ps = __uint_as_float(rr[0]) + __uint_as_float(rr[1]); }
;   l_reg = l_reg * alpha + ps;
;     ...
;   PK4(p0, 0, pa0); PK4(p0, 8, pa1); PK4(p1, 0, pa2); PK4(p1, 8, pa3);
;     ...
; }
; __device__ __forceinline__ void qkt(f32x16& p0, f32x16& p1, const bf16_t* Ks, const bf16x8* qr, int r32, int hi) {
;   p0 = f32x16{}; p1 = f32x16{};
; #pragma unroll
;   for (int d0 = 0; d0 < 8; ++d0) { int cb = (d0 * 16 + hi * 8) * 2;
;     bf16x8 b0 = *reinterpret_cast<const bf16x8*>((const char*)Ks + KSWZ(r32, cb));
;     bf16x8 b1 = *reinterpret_cast<const bf16x8*>((const char*)Ks + KSWZ(32 + r32, cb));
;     p0 = __builtin_amdgcn_mfma_f32_32x32x16_bf16(b0, qr[d0], p0, 0, 0, 0);
;     p1 = __builtin_amdgcn_mfma_f32_32x32x16_bf16(b1, qr[d0], p1, 0, 0, 0); }
; template <int DA, int DB> __device__ __forceinline__ void pv_pair(f32x16& oa, f32x16& ob, int vb, bf16x8 pa0, bf16x8 pa1, bf16x8 pa2, bf16x8 pa3) {
;     ...
;   { const s16x4 al0 = tr_read<v_rd_off(DA, 0, 0)>(vb), ah0 = tr_read<v_rd_off(DA, 0, 1)>(vb), al1 = tr_read<v_rd_off(DA, 1, 0)>(vb), ah1 = tr_read<v_rd_off(DA, 1, 1)>(vb);
;     const s16x4 bl0 = tr_read<v_rd_off(DB, 0, 0)>(vb), bh0 = tr_read<v_rd_off(DB, 0, 1)>(vb), bl1 = tr_read<v_rd_off(DB, 1, 0)>(vb), bh1 = tr_read<v_rd_off(DB, 1, 1)>(vb);
;     asm volatile("s_waitcnt lgkmcnt(0)" ::: "memory"); SBAR();
.LBB0_1536:
	ds_read_b128 v[64:67], v204 offset:49152
	ds_read_b128 v[68:71], v204 offset:57344
	v_exp_f32_e32 v156, v156
	v_exp_f32_e32 v157, v157
	v_exp_f32_e32 v154, v154
	s_waitcnt lgkmcnt(1)
	v_mfma_f32_32x32x16_bf16 v[80:95], v[64:67], v[124:127], 0
	v_exp_f32_e32 v155, v155
	v_exp_f32_e32 v150, v150
	s_waitcnt lgkmcnt(0)
	v_mfma_f32_32x32x16_bf16 v[64:79], v[68:71], v[124:127], 0
	ds_read_b128 v[124:127], v205 offset:49152
	ds_read_b128 v[128:131], v205 offset:57344
	ds_read_b128 v[132:135], v206 offset:49152
	ds_read_b128 v[136:139], v206 offset:57344
	s_waitcnt lgkmcnt(3)
	v_mfma_f32_32x32x16_bf16 v[80:95], v[124:127], v[120:123], v[80:95]
	ds_read_b128 v[124:127], v207 offset:49152
	ds_read_b128 v[140:143], v207 offset:57344
	ds_read_b128 v[218:221], v208 offset:49152
	ds_read_b128 v[222:225], v208 offset:57344
	ds_read_b128 v[226:229], v209 offset:49152
	ds_read_b128 v[230:233], v209 offset:57344
	ds_read_b128 v[234:237], v210 offset:49152
	ds_read_b128 v[238:241], v210 offset:57344
	s_waitcnt lgkmcnt(10)
	v_mfma_f32_32x32x16_bf16 v[64:79], v[128:131], v[120:123], v[64:79]
	ds_read_b128 v[120:123], v211 offset:49152
	ds_read_b128 v[128:131], v211 offset:57344
	s_waitcnt lgkmcnt(11)
	v_mfma_f32_32x32x16_bf16 v[80:95], v[132:135], v[116:119], v[80:95]
	v_exp_f32_e32 v132, v151
	v_exp_f32_e32 v133, v148
	v_exp_f32_e32 v134, v149
	v_exp_f32_e32 v135, v144
	v_exp_f32_e32 v144, v145
	v_exp_f32_e32 v145, v158
	v_exp_f32_e32 v148, v159
	s_waitcnt lgkmcnt(10)
	v_mfma_f32_32x32x16_bf16 v[64:79], v[136:139], v[116:119], v[64:79]
	v_add_f32_e32 v116, 0, v175
	v_add_f32_e32 v116, v191, v116
	v_add_f32_e32 v116, v173, v116
	v_add_f32_e32 v116, v190, v116
	v_add_f32_e32 v116, v172, v116
	v_add_f32_e32 v116, v174, v116
	v_add_f32_e32 v116, v170, v116
	s_waitcnt lgkmcnt(9)
	v_mfma_f32_32x32x16_bf16 v[80:95], v[124:127], v[112:115], v[80:95]
	v_add_f32_e32 v116, v171, v116
	v_add_f32_e32 v116, v167, v116
	v_add_f32_e32 v116, v169, v116
	v_exp_f32_e32 v118, v152
	v_exp_f32_e32 v119, v153
	v_exp_f32_e32 v136, v146
	v_exp_f32_e32 v137, v147
	s_waitcnt lgkmcnt(8)
	v_mfma_f32_32x32x16_bf16 v[64:79], v[140:143], v[112:115], v[64:79]
	v_add_f32_e32 v112, v166, v116
	v_add_f32_e32 v112, v168, v112
	v_add_f32_e32 v112, v163, v112
	v_add_f32_e32 v112, v164, v112
	v_add_f32_e32 v112, v162, v112
	v_add_f32_e32 v112, v165, v112
	v_add_f32_e32 v112, v156, v112
	s_waitcnt lgkmcnt(7)
	v_mfma_f32_32x32x16_bf16 v[80:95], v[218:221], v[108:111], v[80:95]
	v_add_f32_e32 v112, v157, v112
	v_add_f32_e32 v112, v154, v112
	v_add_f32_e32 v112, v155, v112
	v_add_f32_e32 v112, v150, v112
	v_add_f32_e32 v112, v132, v112
	v_add_f32_e32 v112, v133, v112
	v_add_f32_e32 v112, v134, v112
	s_waitcnt lgkmcnt(6)
	v_mfma_f32_32x32x16_bf16 v[64:79], v[222:225], v[108:111], v[64:79]
	v_add_f32_e32 v108, v135, v112
	v_add_f32_e32 v108, v144, v108
	v_add_f32_e32 v108, v145, v108
	v_add_f32_e32 v108, v148, v108
	v_add_f32_e32 v108, v118, v108
	v_add_f32_e32 v108, v119, v108
	v_add_f32_e32 v108, v136, v108
	s_waitcnt lgkmcnt(5)
	v_mfma_f32_32x32x16_bf16 v[80:95], v[226:229], v[104:107], v[80:95]
	v_add_f32_e32 v108, v137, v108
	v_mov_b32_e32 v109, v108
	s_nop 1
	v_permlane32_swap_b32_e32 v108, v109
	v_cvt_pk_bf16_f32 v110, v175, v191
	v_cvt_pk_bf16_f32 v111, v173, v190
	v_cvt_pk_bf16_f32 v112, v172, v174
	s_waitcnt lgkmcnt(4)
	v_mfma_f32_32x32x16_bf16 v[64:79], v[230:233], v[104:107], v[64:79]
	v_cvt_pk_bf16_f32 v113, v170, v171
	v_cvt_pk_bf16_f32 v104, v167, v169
	v_cvt_pk_bf16_f32 v105, v166, v168
	v_cvt_pk_bf16_f32 v106, v163, v164
	v_cvt_pk_bf16_f32 v107, v162, v165
	v_cvt_pk_bf16_f32 v114, v156, v157
	v_cvt_pk_bf16_f32 v115, v154, v155
	s_waitcnt lgkmcnt(3)
	v_mfma_f32_32x32x16_bf16 v[80:95], v[234:237], v[100:103], v[80:95]
	v_cvt_pk_bf16_f32 v116, v150, v132
	v_cvt_pk_bf16_f32 v117, v133, v134
	v_permlane32_swap_b32_e32 v110, v112
	v_permlane32_swap_b32_e32 v111, v113
	v_permlane32_swap_b32_e32 v104, v106
	s_waitcnt lgkmcnt(2)
	v_mfma_f32_32x32x16_bf16 v[64:79], v[238:241], v[100:103], v[64:79]
	v_cvt_pk_bf16_f32 v100, v135, v144
	v_cvt_pk_bf16_f32 v101, v145, v148
	v_cvt_pk_bf16_f32 v102, v118, v119
	v_cvt_pk_bf16_f32 v103, v136, v137
	v_permlane32_swap_b32_e32 v105, v107
	v_permlane32_swap_b32_e32 v114, v116
	s_waitcnt lgkmcnt(1)
	v_mfma_f32_32x32x16_bf16 v[80:95], v[120:123], v[96:99], v[80:95]
	v_permlane32_swap_b32_e32 v115, v117
	v_permlane32_swap_b32_e32 v100, v102
	v_permlane32_swap_b32_e32 v101, v103
	s_waitcnt lgkmcnt(0)
	v_mfma_f32_32x32x16_bf16 v[64:79], v[128:131], v[96:99], v[64:79]
	ds_read_b64_tr_b16 v[96:97], v196 offset:0
	ds_read_b64_tr_b16 v[98:99], v196 offset:0x800
	ds_read_b64_tr_b16 v[118:119], v196 offset:0x1000
	ds_read_b64_tr_b16 v[120:121], v196 offset:0x1800
	ds_read_b64_tr_b16 v[122:123], v196 offset:0x200
	ds_read_b64_tr_b16 v[124:125], v196 offset:0xa00
	ds_read_b64_tr_b16 v[126:127], v196 offset:0x1200
	ds_read_b64_tr_b16 v[128:129], v196 offset:0x1a00
	s_nop 0
	s_waitcnt lgkmcnt(6)
	v_mfma_f32_32x32x16_bf16 v[0:15], v[110:113], v[96:99], v[0:15]
	ds_read_b64_tr_b16 v[96:97], v196 offset:0x2000
	ds_read_b64_tr_b16 v[98:99], v196 offset:0x2800
	s_waitcnt lgkmcnt(4)
; __device__ __forceinline__ void partialSM(f32x16& p0, f32x16& p1, float& m_reg, float& mn, float& alpha) {
;   constexpr float C = SCALE * 1.4426950408889634f;
;   float pmax = p0[0];
; #pragma unroll
;   for (int r = 1; r < 16; ++r) pmax = fmaxf(pmax, p0[r]);
; #pragma unroll
;   for (int r = 0; r < 16; ++r) pmax = fmaxf(pmax, p1[r]);
;   { auto rr = __builtin_amdgcn_permlane32_swap(__float_as_uint(pmax), __float_as_uint(pmax), false, false);
;     pmax = fmaxf(__uint_as_float(rr[0]), __uint_as_float(rr[1])); }
; template <int DA, int DB> __device__ __forceinline__ void pv_pair(f32x16& oa, f32x16& ob, int vb, bf16x8 pa0, bf16x8 pa1, bf16x8 pa2, bf16x8 pa3) {
;     ...
;   { const s16x4 al0 = tr_read<v_rd_off(DA, 0, 0)>(vb), ah0 = tr_read<v_rd_off(DA, 0, 1)>(vb), al1 = tr_read<v_rd_off(DA, 1, 0)>(vb), ah1 = tr_read<v_rd_off(DA, 1, 1)>(vb);
;     const s16x4 bl0 = tr_read<v_rd_off(DB, 0, 0)>(vb), bh0 = tr_read<v_rd_off(DB, 0, 1)>(vb), bl1 = tr_read<v_rd_off(DB, 1, 0)>(vb), bh1 = tr_read<v_rd_off(DB, 1, 1)>(vb);
;     asm volatile("s_waitcnt lgkmcnt(0)" ::: "memory"); SBAR();
;     oa = __builtin_amdgcn_mfma_f32_32x32x16_bf16(pa0, PK(al0, ah0), oa, 0, 0, 0); ob = __builtin_amdgcn_mfma_f32_32x32x16_bf16(pa0, PK(bl0, bh0), ob, 0, 0, 0);
;     oa = __builtin_amdgcn_mfma_f32_32x32x16_bf16(pa1, PK(al1, ah1), oa, 0, 0, 0); ob = __builtin_amdgcn_mfma_f32_32x32x16_bf16(pa1, PK(bl1, bh1), ob, 0, 0, 0); }
;   { const s16x4 al2 = tr_read<v_rd_off(DA, 2, 0)>(vb), ah2 = tr_read<v_rd_off(DA, 2, 1)>(vb), al3 = tr_read<v_rd_off(DA, 3, 0)>(vb), ah3 = tr_read<v_rd_off(DA, 3, 1)>(vb);
;     const s16x4 bl2 = tr_read<v_rd_off(DB, 2, 0)>(vb), bh2 = tr_read<v_rd_off(DB, 2, 1)>(vb), bl3 = tr_read<v_rd_off(DB, 3, 0)>(vb), bh3 = tr_read<v_rd_off(DB, 3, 1)>(vb);
;     asm volatile("s_waitcnt lgkmcnt(0)" ::: "memory"); SBAR();
;     oa = __builtin_amdgcn_mfma_f32_32x32x16_bf16(pa2, PK(al2, ah2), oa, 0, 0, 0); ob = __builtin_amdgcn_mfma_f32_32x32x16_bf16(pa2, PK(bl2, bh2), ob, 0, 0, 0);
;     oa = __builtin_amdgcn_mfma_f32_32x32x16_bf16(pa3, PK(al3, ah3), oa, 0, 0, 0); ob = __builtin_amdgcn_mfma_f32_32x32x16_bf16(pa3, PK(bl3, bh3), ob, 0, 0, 0); }
;     ...
; }
; __device__ __forceinline__ void pv_d0(f32x16* o, int vb, bf16x8 pa0, bf16x8 pa1, bf16x8 pa2, bf16x8 pa3) {
;   pv_pair<0, 1>(o[0], o[1], vb, pa0, pa1, pa2, pa3); pv_pair<2, 3>(o[2], o[3], vb, pa0, pa1, pa2, pa3);
	v_mfma_f32_32x32x16_bf16 v[48:63], v[110:113], v[122:125], v[48:63]
	v_mfma_f32_32x32x16_bf16 v[0:15], v[104:107], v[118:121], v[0:15]
	ds_read_b64_tr_b16 v[118:119], v196 offset:0x3000
	ds_read_b64_tr_b16 v[120:121], v196 offset:0x3800
	ds_read_b64_tr_b16 v[122:123], v196 offset:0x2200
	ds_read_b64_tr_b16 v[124:125], v196 offset:0x2a00
	ds_read_b64_tr_b16 v[130:131], v196 offset:0x3200
	ds_read_b64_tr_b16 v[132:133], v196 offset:0x3a00
	s_waitcnt lgkmcnt(8)
	v_mfma_f32_32x32x16_bf16 v[48:63], v[104:107], v[126:129], v[48:63]
	s_waitcnt lgkmcnt(6)
	v_mfma_f32_32x32x16_bf16 v[0:15], v[114:117], v[96:99], v[0:15]
	ds_read_b64_tr_b16 v[96:97], v196 offset:0x400
	ds_read_b64_tr_b16 v[98:99], v196 offset:0xc00
	s_waitcnt lgkmcnt(4)
	v_mfma_f32_32x32x16_bf16 v[48:63], v[114:117], v[122:125], v[48:63]
	v_mfma_f32_32x32x16_bf16 v[0:15], v[100:103], v[118:121], v[0:15]
	ds_read_b64_tr_b16 v[118:119], v196 offset:0x1400
	ds_read_b64_tr_b16 v[120:121], v196 offset:0x1c00
	ds_read_b64_tr_b16 v[122:123], v196 offset:0x600
	ds_read_b64_tr_b16 v[124:125], v196 offset:0xe00
	ds_read_b64_tr_b16 v[126:127], v196 offset:0x1600
	ds_read_b64_tr_b16 v[128:129], v196 offset:0x1e00
	s_waitcnt lgkmcnt(8)
	v_mfma_f32_32x32x16_bf16 v[48:63], v[100:103], v[130:133], v[48:63]
	s_waitcnt lgkmcnt(6)
	v_mfma_f32_32x32x16_bf16 v[32:47], v[110:113], v[96:99], v[32:47]
	ds_read_b64_tr_b16 v[96:97], v196 offset:0x2400
	ds_read_b64_tr_b16 v[98:99], v196 offset:0x2c00
	s_waitcnt lgkmcnt(4)
	v_mfma_f32_32x32x16_bf16 v[16:31], v[110:113], v[122:125], v[16:31]
	ds_read_b64_tr_b16 v[110:111], v196 offset:0x3400
	ds_read_b64_tr_b16 v[112:113], v196 offset:0x3c00
	v_mfma_f32_32x32x16_bf16 v[32:47], v[104:107], v[118:121], v[32:47]
	ds_read_b64_tr_b16 v[118:119], v196 offset:0x2600
	ds_read_b64_tr_b16 v[120:121], v196 offset:0x2e00
	ds_read_b64_tr_b16 v[122:123], v196 offset:0x3600
	ds_read_b64_tr_b16 v[124:125], v196 offset:0x3e00
	s_waitcnt lgkmcnt(8)
	v_mfma_f32_32x32x16_bf16 v[16:31], v[104:107], v[126:129], v[16:31]
	v_max_f32_e32 v104, v81, v81
	v_max_f32_e32 v105, v80, v80
	v_max_f32_e32 v104, v105, v104
	v_max3_f32 v104, v104, v82, v83
	v_max3_f32 v104, v104, v84, v85
	s_waitcnt lgkmcnt(6)
	v_mfma_f32_32x32x16_bf16 v[32:47], v[114:117], v[96:99], v[32:47]
	v_max3_f32 v96, v104, v86, v87
	v_max3_f32 v96, v96, v88, v89
	v_max3_f32 v96, v96, v90, v91
	v_max3_f32 v96, v96, v92, v93
	v_max3_f32 v96, v96, v94, v95
	v_max3_f32 v96, v96, v64, v65
	v_max3_f32 v96, v96, v66, v67
	v_max3_f32 v96, v96, v68, v69
	v_max3_f32 v96, v96, v70, v71
	v_max3_f32 v96, v96, v72, v73
	s_waitcnt lgkmcnt(2)
	v_mfma_f32_32x32x16_bf16 v[16:31], v[114:117], v[118:121], v[16:31]
	v_max3_f32 v96, v96, v74, v75
	v_max3_f32 v96, v96, v76, v77
	v_max3_f32 v96, v96, v78, v79
	v_mov_b32_e32 v97, v96
	s_nop 1
	v_permlane32_swap_b32_e32 v96, v97
	v_max_f32_e32 v97, v97, v97
	v_max_f32_e32 v96, v96, v96
	v_max_f32_e32 v96, v96, v97
	v_max_f32_e32 v97, v160, v160
	v_max_f32_e32 v97, v97, v96
	v_mfma_f32_32x32x16_bf16 v[32:47], v[100:103], v[110:113], v[32:47]
	v_sub_f32_e32 v98, v96, v160
	v_sub_f32_e32 v96, v160, v97
	v_mul_f32_e32 v96, 0x3e0293ee, v96
	v_exp_f32_e32 v96, v96
	v_cmp_ge_f32_e32 vcc, s62, v98
	s_cmp_eq_u64 vcc, exec
	s_cselect_b64 s[6:7], -1, 0
	s_waitcnt lgkmcnt(0)
	v_mfma_f32_32x32x16_bf16 v[16:31], v[100:103], v[122:125], v[16:31]
	v_cndmask_b32_e64 v96, v96, 1.0, s[6:7]
	v_cmp_gt_f32_e32 vcc, 1.0, v96
	s_barrier
	s_cbranch_vccz .LBB0_1540
	s_and_saveexec_b64 s[18:19], s[4:5]
	ds_write_b32 v198, v96 offset:128
	s_or_b64 exec, exec, s[18:19]
	s_waitcnt lgkmcnt(0)
	v_add_u32_e32 v106, v195, v197
	ds_read_b128 v[98:101], v106 offset:224
	ds_read_b128 v[102:105], v106 offset:192
	ds_read_b128 v[110:113], v106 offset:160
	ds_read_b128 v[114:117], v106 offset:128
	s_waitcnt lgkmcnt(3)
	v_pk_mul_f32 v[12:13], v[12:13], v[98:99]
	s_waitcnt lgkmcnt(2)
	v_pk_mul_f32 v[8:9], v[8:9], v[102:103]
	s_waitcnt lgkmcnt(1)
	v_pk_mul_f32 v[4:5], v[4:5], v[110:111]
	v_pk_mul_f32 v[14:15], v[14:15], v[100:101]
	v_pk_mul_f32 v[10:11], v[10:11], v[104:105]
	v_pk_mul_f32 v[6:7], v[6:7], v[112:113]
	s_waitcnt lgkmcnt(0)
	v_pk_mul_f32 v[2:3], v[2:3], v[116:117]
	v_pk_mul_f32 v[0:1], v[0:1], v[114:115]
	v_pk_mul_f32 v[60:61], v[60:61], v[98:99]
	v_pk_mul_f32 v[56:57], v[56:57], v[102:103]
	v_pk_mul_f32 v[52:53], v[52:53], v[110:111]
	v_pk_mul_f32 v[62:63], v[62:63], v[100:101]
	v_pk_mul_f32 v[58:59], v[58:59], v[104:105]
	v_pk_mul_f32 v[54:55], v[54:55], v[112:113]
	v_pk_mul_f32 v[50:51], v[50:51], v[116:117]
	v_pk_mul_f32 v[48:49], v[48:49], v[114:115]
	v_pk_mul_f32 v[44:45], v[44:45], v[98:99]
	v_pk_mul_f32 v[40:41], v[40:41], v[102:103]
	v_pk_mul_f32 v[36:37], v[36:37], v[110:111]
	v_pk_mul_f32 v[46:47], v[46:47], v[100:101]
	v_pk_mul_f32 v[42:43], v[42:43], v[104:105]
	v_pk_mul_f32 v[38:39], v[38:39], v[112:113]
	v_pk_mul_f32 v[34:35], v[34:35], v[116:117]
	v_pk_mul_f32 v[32:33], v[32:33], v[114:115]
	v_pk_mul_f32 v[28:29], v[28:29], v[98:99]
	v_pk_mul_f32 v[24:25], v[24:25], v[102:103]
	v_pk_mul_f32 v[20:21], v[20:21], v[110:111]
	v_pk_mul_f32 v[30:31], v[30:31], v[100:101]
	v_pk_mul_f32 v[26:27], v[26:27], v[104:105]
	v_pk_mul_f32 v[22:23], v[22:23], v[112:113]
	v_pk_mul_f32 v[18:19], v[18:19], v[116:117]
	v_pk_mul_f32 v[16:17], v[16:17], v[114:115]
